# GEMM K-loop per-segment s_setprio flips removed; one static s_setprio 1 for waves 0-3 for the duration of each GEMM job (reset to 0 at job end)
# speedup vs baseline: 1.0139x; 1.0139x over previous
; #define LAS __attribute__((address_space(3)))
; __device__ __forceinline__ int tid_opaque() { int t = threadIdx.x; asm volatile("" : "+v"(t)); return t; }
; __device__ __forceinline__ void gemm_phase(LAS unsigned char* lds, CParams& p, const Job& jb) {
;     const int tid = tid_opaque(), wid = __builtin_amdgcn_readfirstlane(tid >> 6), lane = tid & 63, wr = wid >> 2, wc = wid & 3, fr = lane & 15, fq = lane >> 4;
;     Sched S; S.init(jb);
;     const int K = jb.K, nt = K / BK, lda = jb.lda, ldb = jb.ldb;
;     unsigned voffA[2], voffB[2];
; #pragma unroll
;     for (int i = 0; i < 2; ++i) { int R, C; stage_rc(tid * 16 + i * 8192, R, C); const int Rb = (R & ~31) + perm32(R & 31);
;         voffA[i] = (unsigned)(R * lda + C) * 2u; voffB[i] = (unsigned)(Rb * ldb + C) * 2u; }
;     const size_t kstep = (size_t)(BK * 2);
;     const size_t hstepA = (size_t)HALF * lda * 2, hstepB = (size_t)HALF * ldb * 2;
;     const unsigned ldsw = (unsigned)wid * 1024u;
;     const int aoff = lds_byte(wr * 64 + fr, fq * 8), boff = lds_byte(wc * 32 + fr, fq * 8);
;     ...
;     Unit cur, nxt; int ui = 0;
;     if (!S.next(0, cur)) return;
.LBB0_515:
	v_readfirstlane_b32 s101, v192
	s_lshr_b32 s101, s101, 8
	s_cmp_eq_u32 s101, 0
	s_cbranch_scc0 .Lprio_skip
	s_setprio 1

; #define PG8_WAIT_V(n) asm volatile("s_waitcnt vmcnt(" #n ")" ::: "memory")
; #define PG8_BAR __builtin_amdgcn_s_barrier()
; __device__ __forceinline__ void gemm_phase(LAS unsigned char* lds, CParams& p, const Job& jb) {
;     ...
;     PG8_WAIT_V(0);
;     if (wr == 0) PG8_BAR;
;     PG8_BAR;
.LBB0_913:
	s_setprio 0
	s_waitcnt vmcnt(0)
	v_readlane_b32 s0, v244, 14
	v_readlane_b32 s60, v245, 57
	v_readlane_b32 s64, v245, 59
	v_readlane_b32 s66, v245, 61
	v_readlane_b32 s74, v245, 63
	v_readlane_b32 s76, v244, 1
	v_readlane_b32 s82, v244, 3
	v_readlane_b32 s86, v244, 5
	s_cmpk_gt_u32 s0, 0xff
	v_readlane_b32 s61, v245, 58
	v_readlane_b32 s65, v245, 60
	v_readlane_b32 s67, v245, 62
	v_readlane_b32 s75, v244, 0
	v_readlane_b32 s77, v244, 2
	v_readlane_b32 s83, v244, 4
	v_readlane_b32 s87, v244, 6
	v_readlane_b32 s69, v244, 7
	s_movk_i32 s85, 0x1a00
	s_movk_i32 s94, 0xff
	s_mov_b32 s96, 0xf800000
	s_movk_i32 s33, 0x89
	s_mov_b32 s42, 0x88888889
	s_mov_b64 s[44:45], 0x800
	v_readlane_b32 s43, v244, 8
	v_readlane_b32 s18, v244, 13
	s_cbranch_scc1 .LBB0_512
	s_barrier
	s_branch .LBB0_512
